# v62 + SWA item loops (both layers): next item's address arithmetic and Q/sink/first K,V-tile loads issued from inside the current item's output epilogue; later items enter at a copy of the post-load p
# baseline (speedup 1.0000x reference)
; DI unsigned pack2(float a, float b) { f32x2_t v = {a, b}; bf16x2_t r = __builtin_convertvector(v, bf16x2_t); return __builtin_bit_cast(unsigned, r); }
; DI void attn_write_staged(const f32x16& o0, const f32x16& o1, bf16_t* og, const bf16_t* z, size_t tok0, int head, int lane, bf16_t* wl) {
;   const int q = lane & 31, h = lane >> 5;
; #pragma unroll
;   for (int dt = 0; dt < 2; ++dt)
; #pragma unroll
;     for (int q4 = 0; q4 < 4; ++q4) {
;       const f32x16& o = dt ? o1 : o0;
;       *(uint2*)(wl + q * 72 + dt * 32 + 8 * q4 + 4 * h) = make_uint2(pack2(o[4 * q4], o[4 * q4 + 1]), pack2(o[4 * q4 + 2], o[4 * q4 + 3]));
;     }
; DI void phase_attn_swa(const Params& P, const float* sinks, bf16_t* og, unsigned char* smem, int L, int G) {
;     ...
;   for (int it = L; it < 4096; it += G) {
;     int qt, bg; gqa_item(it, L, G, gi, qt, bg);
;     const int b = bg >> 2, g = bg & 3;
;     const int t0 = qt * 32, t = t0 + r, head = g * 4 + w;
;     const size_t tok = (size_t)b * SEQ + t;
;     bf16x8 qf[4];
; #pragma unroll
;     for (int ks = 0; ks < 4; ++ks) qf[ks] = *(const bf16x8*)(big + SW_Q + tok * 1024 + head * 64 + ks * 16 + 8 * h);
;     f32x16 o0, o1, s[2]; o_zero(o0, o1);
;     float m = sinks[head] * LOG2E, l = 1.f;
;     const bf16_t* kb = big + SW_K + (size_t)b * SEQ * 256 + g * 64;
;     const bf16_t* vb = big + SW_VT + (size_t)((b * 4 + g) * 64) * SEQ;
;     const int jlo = (t0 - 127 > 0 ? t0 - 127 : 0) >> 6, jhi = (t0 + 31) >> 6;
;     KVR R; kv64_fetch(R, kb, 256, vb, SEQ, jlo * 64, true, tid);
;     __syncthreads();
;     kv64_store(R, sK, sVt, tid);
;     if (jlo < jhi) kv64_fetch(R, kb, 256, vb, SEQ, jlo * 64 + 64, true, tid);
.LBB0_337:
	s_mov_b32 s41, s39
	v_lshlrev_b32_e32 v35, 6, v173
	v_lshl_add_u64 v[32:33], v[148:149], 0, s[40:41]
	v_or_b32_e32 v35, v35, v130
	v_or_b32_e32 v36, v32, v132
	v_mov_b32_e32 v37, v33
	v_lshlrev_b64 v[40:41], 11, v[36:37]
	v_lshlrev_b32_e32 v35, 1, v35
	v_or_b32_e32 v40, v40, v35
	v_lshl_add_u64 v[36:37], s[36:37], 0, v[40:41]
	v_mov_b32_e32 v254, 0x4000
	v_mov_b32_e32 v255, 0
	v_lshl_add_u64 v[248:249], v[36:37], 0, v[254:255]
	v_lshl_add_u64 v[250:251], v[248:249], 0, v[254:255]
	v_lshl_add_u64 v[252:253], v[250:251], 0, v[254:255]
	global_load_dwordx4 v[36:39], v[36:37], off
	global_load_dwordx4 v[96:99], v[248:249], off
	global_load_dwordx4 v[100:103], v[250:251], off
	global_load_dwordx4 v[104:107], v[252:253], off
	s_add_i32 s98, s45, s74
	s_cmpk_gt_i32 s98, 0xfff
	s_cbranch_scc1 .Lmy_sw338_nopf
	s_and_b64 vcc, exec, s[2:3]
	s_cbranch_vccz .Lmy_sw338_340
	s_ashr_i32 s100, s98, 6
	s_sub_i32 s41, 63, s100
	s_lshl_b32 s100, s98, 1
	s_and_b32 s100, s100, 0x7e
	v_add_u32_e32 v220, s100, v131
	s_cbranch_execz .Lmy_sw338_341
	s_branch .Lmy_sw338_342
.Lmy_sw338_340:
.Lmy_sw338_341:
	s_ashr_i32 s100, s98, 8
	s_and_b32 s100, s100, -2
	s_bitcmp0_b32 s98, 8
	v_add_u32_e32 v220, s100, v139
	s_cselect_b32 s41, s33, s42
.Lmy_sw338_342:
	v_ashrrev_i32_e32 v218, 2, v220
	s_lshl_b32 s40, s41, 5
	v_ashrrev_i32_e32 v219, 31, v218
	v_or_b32_e32 v150, s40, v135
	v_lshlrev_b64 v[148:149], 11, v[218:219]
	v_mov_b32_e32 v151, v129
	v_and_b32_e32 v221, 3, v220
	v_lshl_add_u64 v[222:223], v[148:149], 0, v[150:151]
	v_lshl_or_b32 v173, v221, 2, v133
	v_lshlrev_b64 v[222:223], 11, v[222:223]
	s_max_i32 s100, s40, 0x7f
	v_lshl_add_u64 v[222:223], s[76:77], 0, v[222:223]
	v_lshlrev_b32_e32 v128, 7, v173
	v_lshlrev_b64 v[218:219], 20, v[218:219]
	v_lshlrev_b32_e32 v220, 6, v220
	s_add_i32 s46, s100, 0xffffff81
	v_lshl_add_u64 v[222:223], v[222:223], 0, v[128:129]
	v_lshl_add_u64 v[218:219], s[30:31], 0, v[218:219]
	v_lshlrev_b32_e32 v128, 7, v221
	v_ashrrev_i32_e32 v221, 31, v220
	s_and_b32 s38, s46, 0xffffffc0
	v_lshl_add_u64 v[230:231], v[222:223], 0, v[140:141]
	v_lshlrev_b32_e32 v222, 2, v173
	v_lshl_add_u64 v[218:219], v[218:219], 0, v[128:129]
	v_lshlrev_b64 v[220:221], 12, v[220:221]
	v_or_b32_e32 v128, s38, v158
	global_load_dwordx4 v[64:67], v[230:231], off
	global_load_dwordx4 v[68:71], v[230:231], off offset:32
	global_load_dword v228, v222, s[14:15]
	v_lshl_add_u64 v[222:223], s[34:35], 0, v[220:221]
	v_lshlrev_b64 v[220:221], 9, v[128:129]
	v_or_b32_e32 v128, s38, v159
	v_lshl_add_u64 v[220:221], v[218:219], 0, v[220:221]
	v_lshlrev_b64 v[224:225], 9, v[128:129]
	v_lshl_add_u64 v[220:221], v[220:221], 0, v[142:143]
	v_lshl_add_u64 v[224:225], v[218:219], 0, v[224:225]
	v_lshl_add_u64 v[224:225], v[224:225], 0, v[142:143]
	global_load_dwordx4 v[80:83], v[220:221], off
	global_load_dwordx4 v[84:87], v[224:225], off
	v_lshl_add_u64 v[220:221], v[222:223], 0, v[144:145]
	s_lshl_b64 s[100:101], s[38:39], 1
	v_lshl_add_u64 v[224:225], v[220:221], 0, s[100:101]
	v_lshl_add_u64 v[224:225], v[224:225], 0, v[142:143]
	v_lshl_add_u64 v[222:223], v[222:223], 0, v[146:147]
	global_load_dwordx4 v[88:91], v[224:225], off
	v_lshl_add_u64 v[226:227], v[222:223], 0, s[100:101]
	v_lshl_add_u64 v[226:227], v[226:227], 0, v[142:143]
	global_load_dwordx4 v[92:95], v[226:227], off
	global_load_dwordx4 v[72:75], v[230:231], off offset:64
	global_load_dwordx4 v[76:79], v[230:231], off offset:96
	s_branch .Lmy_sw338_join
.Lmy_sw338_nopf:
	global_load_dword v218, v[248:249], off
	global_load_dword v218, v[248:249], off
	global_load_dword v218, v[248:249], off
	global_load_dword v218, v[248:249], off
	global_load_dword v218, v[248:249], off
	global_load_dword v218, v[248:249], off
	global_load_dword v218, v[248:249], off
	global_load_dword v218, v[248:249], off
	global_load_dword v218, v[248:249], off
.Lmy_sw338_join:
	v_div_scale_f32 v42, s[0:1], v34, v34, 1.0
	v_rcp_f32_e32 v43, v42
	v_div_scale_f32 v44, vcc, 1.0, v34, 1.0
	v_add_u32_e32 v45, 0xa000, v166
	v_fma_f32 v46, -v42, v43, 1.0
	v_fmac_f32_e32 v43, v46, v43
	v_mul_f32_e32 v46, v44, v43
	v_fma_f32 v47, -v42, v46, v44
	v_fmac_f32_e32 v46, v47, v43
	v_fma_f32 v42, -v42, v46, v44
	v_div_fmas_f32 v42, v42, v43, v46
	v_div_fixup_f32 v34, v42, v34, 1.0
	v_pk_mul_f32 v[0:1], v[34:35], v[0:1] op_sel_hi:[0,1]
	v_pk_mul_f32 v[2:3], v[34:35], v[2:3] op_sel_hi:[0,1]
	v_pk_mul_f32 v[4:5], v[34:35], v[4:5] op_sel_hi:[0,1]
	v_pk_mul_f32 v[20:21], v[20:21], v[34:35] op_sel_hi:[1,0]
	v_pk_mul_f32 v[6:7], v[34:35], v[6:7] op_sel_hi:[0,1]
	v_pk_mul_f32 v[22:23], v[22:23], v[34:35] op_sel_hi:[1,0]
	v_pk_mul_f32 v[24:25], v[24:25], v[34:35] op_sel_hi:[1,0]
	v_pk_mul_f32 v[10:11], v[34:35], v[10:11] op_sel_hi:[0,1]
	v_pk_mul_f32 v[26:27], v[26:27], v[34:35] op_sel_hi:[1,0]
	v_pk_mul_f32 v[12:13], v[34:35], v[12:13] op_sel_hi:[0,1]
	v_pk_mul_f32 v[16:17], v[16:17], v[34:35] op_sel_hi:[1,0]
	v_pk_mul_f32 v[18:19], v[18:19], v[34:35] op_sel_hi:[1,0]
	v_pk_mul_f32 v[8:9], v[34:35], v[8:9] op_sel_hi:[0,1]
	v_pk_mul_f32 v[28:29], v[28:29], v[34:35] op_sel_hi:[1,0]
	v_pk_mul_f32 v[14:15], v[34:35], v[14:15] op_sel_hi:[0,1]
	v_pk_mul_f32 v[30:31], v[30:31], v[34:35] op_sel_hi:[1,0]
	v_cvt_pk_bf16_f32 v0, v0, v1
	v_cvt_pk_bf16_f32 v1, v2, v3
	v_cvt_pk_bf16_f32 v2, v4, v5
	v_cvt_pk_bf16_f32 v3, v6, v7
	v_cvt_pk_bf16_f32 v5, v10, v11
	v_cvt_pk_bf16_f32 v6, v12, v13
	v_cvt_pk_bf16_f32 v10, v20, v21
	v_cvt_pk_bf16_f32 v11, v22, v23
	v_cvt_pk_bf16_f32 v12, v24, v25
	v_cvt_pk_bf16_f32 v13, v26, v27
	v_cvt_pk_bf16_f32 v4, v8, v9
	v_cvt_pk_bf16_f32 v7, v14, v15
	v_cvt_pk_bf16_f32 v8, v16, v17
	v_cvt_pk_bf16_f32 v9, v18, v19
	v_cvt_pk_bf16_f32 v14, v28, v29
	v_cvt_pk_bf16_f32 v15, v30, v31
	ds_write2_b64 v45, v[0:1], v[2:3] offset1:2
	ds_write2_b64 v45, v[4:5], v[6:7] offset0:4 offset1:6
	ds_write2_b64 v45, v[8:9], v[10:11] offset0:8 offset1:10
	ds_write2_b64 v45, v[12:13], v[14:15] offset0:12 offset1:14
	ds_read_b128 v[0:3], v167 offset:40960
	ds_read_b128 v[4:7], v167 offset:42112
	s_add_i32 s45, s45, s74
	s_cmpk_gt_i32 s45, 0xfff
	s_waitcnt lgkmcnt(1)
; DI unsigned pack2(float a, float b) { f32x2_t v = {a, b}; bf16x2_t r = __builtin_convertvector(v, bf16x2_t); return __builtin_bit_cast(unsigned, r); }
; DI float bflo(unsigned u) { return __uint_as_float(u << 16); }
; DI float bfhi(unsigned u) { return __uint_as_float(u & 0xffff0000u); }
; DI float siluf_(float x) { return x * __builtin_amdgcn_rcpf(1.f + __expf(-x)); }
; DI void attn_write_staged(const f32x16& o0, const f32x16& o1, bf16_t* og, const bf16_t* z, size_t tok0, int head, int lane, bf16_t* wl) {
;     ...
; #pragma unroll
;   for (int k = 0; k < 4; ++k) {
;     const int ci = lane + 64 * k, row = ci >> 3, c8 = ci & 7;
;     const u32x4 ov = *(const u32x4*)(wl + row * 72 + c8 * 8);
;     const size_t off = (tok0 + row) * 1024 + head * 64 + c8 * 8;
;     const u32x4 zv = ldg16(z + off);
;     u32x4 r;
;     r.x = pack2(bflo(ov.x) * siluf_(bflo(zv.x)), bfhi(ov.x) * siluf_(bfhi(zv.x)));
;     r.y = pack2(bflo(ov.y) * siluf_(bflo(zv.y)), bfhi(ov.y) * siluf_(bfhi(zv.y)));
;     r.z = pack2(bflo(ov.z) * siluf_(bflo(zv.z)), bfhi(ov.z) * siluf_(bfhi(zv.z)));
;     r.w = pack2(bflo(ov.w) * siluf_(bflo(zv.w)), bfhi(ov.w) * siluf_(bfhi(zv.w)));
;     *(u32x4*)(og + off) = r;
;   }
	v_lshlrev_b32_e32 v8, 16, v0
	v_and_b32_e32 v9, 0xffff0000, v0
	v_lshlrev_b32_e32 v0, 16, v1
	v_and_b32_e32 v1, 0xffff0000, v1
	s_waitcnt vmcnt(12)
	v_lshlrev_b32_e32 v10, 16, v36
	v_and_b32_e32 v11, 0xffff0000, v36
	v_lshlrev_b32_e32 v12, 16, v37
	v_and_b32_e32 v13, 0xffff0000, v37
	v_mul_f32_e32 v16, 0xbfb8aa3b, v10
	v_mul_f32_e32 v17, 0xbfb8aa3b, v11
	v_mul_f32_e32 v18, 0xbfb8aa3b, v12
	v_mul_f32_e32 v19, 0xbfb8aa3b, v13
	v_exp_f32_e32 v16, v16
	v_exp_f32_e32 v17, v17
	v_exp_f32_e32 v18, v18
	v_exp_f32_e32 v19, v19
	v_lshlrev_b32_e32 v14, 16, v38
	v_and_b32_e32 v15, 0xffff0000, v38
	v_add_f32_e32 v16, 1.0, v16
	v_add_f32_e32 v17, 1.0, v17
	v_add_f32_e32 v18, 1.0, v18
	v_add_f32_e32 v19, 1.0, v19
	v_mul_f32_e32 v20, 0xbfb8aa3b, v14
	v_mul_f32_e32 v21, 0xbfb8aa3b, v15
	v_rcp_f32_e32 v16, v16
	v_rcp_f32_e32 v17, v17
	v_rcp_f32_e32 v18, v18
	v_rcp_f32_e32 v19, v19
	v_exp_f32_e32 v20, v20
	v_exp_f32_e32 v21, v21
	v_pk_mul_f32 v[10:11], v[16:17], v[10:11]
	v_pk_mul_f32 v[12:13], v[18:19], v[12:13]
	v_add_f32_e32 v20, 1.0, v20
	v_pk_mul_f32 v[8:9], v[10:11], v[8:9]
	v_pk_mul_f32 v[10:11], v[12:13], v[0:1]
	v_add_f32_e32 v1, 1.0, v21
	v_rcp_f32_e32 v20, v20
	v_rcp_f32_e32 v21, v1
	v_lshlrev_b32_e32 v12, 16, v39
	v_cvt_pk_bf16_f32 v0, v8, v9
	v_lshlrev_b32_e32 v8, 16, v2
	v_and_b32_e32 v9, 0xffff0000, v2
	v_and_b32_e32 v13, 0xffff0000, v39
	v_mul_f32_e32 v2, 0xbfb8aa3b, v12
	v_cvt_pk_bf16_f32 v1, v10, v11
	v_pk_mul_f32 v[10:11], v[20:21], v[14:15]
	v_exp_f32_e32 v2, v2
	v_mul_f32_e32 v14, 0xbfb8aa3b, v13
	v_exp_f32_e32 v14, v14
	v_pk_mul_f32 v[8:9], v[10:11], v[8:9]
	v_add_f32_e32 v2, 1.0, v2
	v_rcp_f32_e32 v10, v2
	v_add_f32_e32 v2, 1.0, v14
	v_rcp_f32_e32 v11, v2
	v_cvt_pk_bf16_f32 v2, v8, v9
	v_lshlrev_b32_e32 v8, 16, v3
	v_and_b32_e32 v9, 0xffff0000, v3
	v_pk_mul_f32 v[10:11], v[10:11], v[12:13]
	s_waitcnt lgkmcnt(0)
	v_lshlrev_b32_e32 v12, 16, v4
	v_pk_mul_f32 v[8:9], v[10:11], v[8:9]
	v_or_b32_e32 v10, v32, v136
	v_cvt_pk_bf16_f32 v3, v8, v9
	v_lshl_add_u64 v[8:9], s[94:95], 0, v[40:41]
	global_store_dwordx4 v[8:9], v[0:3], off
	v_mov_b32_e32 v11, v33
	v_and_b32_e32 v13, 0xffff0000, v4
	v_or_b32_e32 v0, v32, v134
	v_mov_b32_e32 v1, v33
	v_lshlrev_b64 v[8:9], 11, v[0:1]
	v_or_b32_e32 v8, v8, v35
	v_lshl_add_u64 v[0:1], s[36:37], 0, v[8:9]
	v_lshlrev_b32_e32 v4, 16, v5
	v_and_b32_e32 v5, 0xffff0000, v5
	v_lshlrev_b32_e32 v14, 16, v6
	v_and_b32_e32 v15, 0xffff0000, v6
	v_lshlrev_b32_e32 v6, 16, v7
	v_and_b32_e32 v7, 0xffff0000, v7
	v_lshlrev_b64 v[10:11], 11, v[10:11]
	v_lshl_add_u64 v[8:9], s[94:95], 0, v[8:9]
	v_or_b32_e32 v10, v10, v35
	v_or_b32_e32 v32, v32, v138
	s_waitcnt vmcnt(12)
	v_mov_b32_e32 v0, v96
	v_mov_b32_e32 v1, v97
	v_mov_b32_e32 v2, v98
	v_mov_b32_e32 v3, v99
	v_lshlrev_b32_e32 v16, 16, v0
	v_and_b32_e32 v17, 0xffff0000, v0
	v_lshlrev_b32_e32 v0, 16, v1
	v_and_b32_e32 v1, 0xffff0000, v1
	v_lshlrev_b32_e32 v18, 16, v2
	v_and_b32_e32 v19, 0xffff0000, v2
	v_lshlrev_b32_e32 v2, 16, v3
	v_and_b32_e32 v3, 0xffff0000, v3
	v_mul_f32_e32 v20, 0xbfb8aa3b, v16
	v_mul_f32_e32 v21, 0xbfb8aa3b, v17
	v_mul_f32_e32 v22, 0xbfb8aa3b, v0
	v_mul_f32_e32 v23, 0xbfb8aa3b, v1
	v_mul_f32_e32 v24, 0xbfb8aa3b, v18
	v_mul_f32_e32 v25, 0xbfb8aa3b, v19
	v_mul_f32_e32 v26, 0xbfb8aa3b, v2
	v_mul_f32_e32 v27, 0xbfb8aa3b, v3
	v_exp_f32_e32 v20, v20
	v_exp_f32_e32 v21, v21
	v_exp_f32_e32 v22, v22
	v_exp_f32_e32 v23, v23
	v_exp_f32_e32 v24, v24
	v_exp_f32_e32 v25, v25
	v_exp_f32_e32 v26, v26
	v_exp_f32_e32 v27, v27
	v_add_f32_e32 v20, 1.0, v20
	v_add_f32_e32 v21, 1.0, v21
	v_add_f32_e32 v22, 1.0, v22
	v_add_f32_e32 v23, 1.0, v23
	v_add_f32_e32 v24, 1.0, v24
	v_add_f32_e32 v25, 1.0, v25
	v_add_f32_e32 v26, 1.0, v26
	v_add_f32_e32 v27, 1.0, v27
	v_rcp_f32_e32 v20, v20
	v_rcp_f32_e32 v21, v21
	v_rcp_f32_e32 v22, v22
	v_rcp_f32_e32 v23, v23
	v_rcp_f32_e32 v24, v24
	v_rcp_f32_e32 v25, v25
	v_rcp_f32_e32 v26, v26
	v_rcp_f32_e32 v27, v27
	v_pk_mul_f32 v[16:17], v[20:21], v[16:17]
	v_pk_mul_f32 v[0:1], v[22:23], v[0:1]
	v_pk_mul_f32 v[18:19], v[24:25], v[18:19]
	v_pk_mul_f32 v[2:3], v[26:27], v[2:3]
	v_pk_mul_f32 v[12:13], v[16:17], v[12:13]
	v_pk_mul_f32 v[4:5], v[0:1], v[4:5]
	v_pk_mul_f32 v[14:15], v[18:19], v[14:15]
	v_pk_mul_f32 v[6:7], v[2:3], v[6:7]
	v_cvt_pk_bf16_f32 v0, v12, v13
	v_cvt_pk_bf16_f32 v1, v4, v5
	v_cvt_pk_bf16_f32 v2, v14, v15
	v_cvt_pk_bf16_f32 v3, v6, v7
	global_store_dwordx4 v[8:9], v[0:3], off
	v_lshlrev_b64 v[12:13], 11, v[32:33]
	ds_read_b128 v[4:7], v167 offset:43264
	v_lshl_add_u64 v[0:1], s[36:37], 0, v[10:11]
	v_lshl_add_u64 v[14:15], s[94:95], 0, v[10:11]
	ds_read_b128 v[8:11], v167 offset:44416
	s_waitcnt lgkmcnt(1)
; DI unsigned pack2(float a, float b) { f32x2_t v = {a, b}; bf16x2_t r = __builtin_convertvector(v, bf16x2_t); return __builtin_bit_cast(unsigned, r); }
; DI float bflo(unsigned u) { return __uint_as_float(u << 16); }
; DI float bfhi(unsigned u) { return __uint_as_float(u & 0xffff0000u); }
; DI float siluf_(float x) { return x * __builtin_amdgcn_rcpf(1.f + __expf(-x)); }
; DI void attn_write_staged(const f32x16& o0, const f32x16& o1, bf16_t* og, const bf16_t* z, size_t tok0, int head, int lane, bf16_t* wl) {
;     ...
; #pragma unroll
;   for (int k = 0; k < 4; ++k) {
;     const int ci = lane + 64 * k, row = ci >> 3, c8 = ci & 7;
;     const u32x4 ov = *(const u32x4*)(wl + row * 72 + c8 * 8);
;     const size_t off = (tok0 + row) * 1024 + head * 64 + c8 * 8;
;     const u32x4 zv = ldg16(z + off);
;     u32x4 r;
;     r.x = pack2(bflo(ov.x) * siluf_(bflo(zv.x)), bfhi(ov.x) * siluf_(bfhi(zv.x)));
;     r.y = pack2(bflo(ov.y) * siluf_(bflo(zv.y)), bfhi(ov.y) * siluf_(bfhi(zv.y)));
;     r.z = pack2(bflo(ov.z) * siluf_(bflo(zv.z)), bfhi(ov.z) * siluf_(bfhi(zv.z)));
;     r.w = pack2(bflo(ov.w) * siluf_(bflo(zv.w)), bfhi(ov.w) * siluf_(bfhi(zv.w)));
;     *(u32x4*)(og + off) = r;
;   }
; DI void phase_attn_swa(const Params& P, const float* sinks, bf16_t* og, unsigned char* smem, int L, int G) {
;     ...
;     __syncthreads();
;     kv64_store(R, sK, sVt, tid);
;     if (jlo < jhi) kv64_fetch(R, kb, 256, vb, SEQ, jlo * 64 + 64, true, tid);
	v_lshlrev_b32_e32 v18, 16, v4
	v_and_b32_e32 v19, 0xffff0000, v4
	v_lshlrev_b32_e32 v4, 16, v5
	v_and_b32_e32 v5, 0xffff0000, v5
	v_lshlrev_b32_e32 v20, 16, v6
	v_and_b32_e32 v21, 0xffff0000, v6
	v_lshlrev_b32_e32 v6, 16, v7
	v_and_b32_e32 v7, 0xffff0000, v7
	v_or_b32_e32 v12, v12, v35
	v_lshl_add_u64 v[16:17], s[36:37], 0, v[12:13]
	s_waitcnt vmcnt(12)
	v_mov_b32_e32 v0, v100
	v_mov_b32_e32 v1, v101
	v_mov_b32_e32 v2, v102
	v_mov_b32_e32 v3, v103
	v_lshlrev_b32_e32 v22, 16, v0
	v_and_b32_e32 v23, 0xffff0000, v0
	v_lshlrev_b32_e32 v0, 16, v1
	v_and_b32_e32 v1, 0xffff0000, v1
	v_lshlrev_b32_e32 v24, 16, v2
	v_and_b32_e32 v25, 0xffff0000, v2
	v_lshlrev_b32_e32 v2, 16, v3
	v_and_b32_e32 v3, 0xffff0000, v3
	v_mul_f32_e32 v26, 0xbfb8aa3b, v22
	v_mul_f32_e32 v27, 0xbfb8aa3b, v23
	v_mul_f32_e32 v28, 0xbfb8aa3b, v0
	v_mul_f32_e32 v29, 0xbfb8aa3b, v1
	v_mul_f32_e32 v30, 0xbfb8aa3b, v24
	v_mul_f32_e32 v31, 0xbfb8aa3b, v25
	v_mul_f32_e32 v32, 0xbfb8aa3b, v2
	v_mul_f32_e32 v33, 0xbfb8aa3b, v3
	v_exp_f32_e32 v26, v26
	v_exp_f32_e32 v27, v27
	v_exp_f32_e32 v28, v28
	v_exp_f32_e32 v29, v29
	v_exp_f32_e32 v30, v30
	v_exp_f32_e32 v31, v31
	v_exp_f32_e32 v32, v32
	v_exp_f32_e32 v33, v33
	v_add_f32_e32 v26, 1.0, v26
	v_add_f32_e32 v27, 1.0, v27
	v_add_f32_e32 v28, 1.0, v28
	v_add_f32_e32 v29, 1.0, v29
	v_add_f32_e32 v30, 1.0, v30
	v_add_f32_e32 v31, 1.0, v31
	v_add_f32_e32 v32, 1.0, v32
	v_add_f32_e32 v33, 1.0, v33
	v_rcp_f32_e32 v26, v26
	v_rcp_f32_e32 v27, v27
	v_rcp_f32_e32 v28, v28
	v_rcp_f32_e32 v29, v29
	v_rcp_f32_e32 v30, v30
	v_rcp_f32_e32 v31, v31
	v_rcp_f32_e32 v32, v32
	v_rcp_f32_e32 v33, v33
	v_pk_mul_f32 v[22:23], v[26:27], v[22:23]
	v_pk_mul_f32 v[0:1], v[28:29], v[0:1]
	v_pk_mul_f32 v[24:25], v[30:31], v[24:25]
	v_pk_mul_f32 v[2:3], v[32:33], v[2:3]
	v_pk_mul_f32 v[18:19], v[22:23], v[18:19]
	v_pk_mul_f32 v[4:5], v[0:1], v[4:5]
	v_pk_mul_f32 v[20:21], v[24:25], v[20:21]
	v_pk_mul_f32 v[6:7], v[2:3], v[6:7]
	v_cvt_pk_bf16_f32 v0, v18, v19
	v_cvt_pk_bf16_f32 v1, v4, v5
	v_cvt_pk_bf16_f32 v2, v20, v21
	v_cvt_pk_bf16_f32 v3, v6, v7
	global_store_dwordx4 v[14:15], v[0:3], off
	v_lshl_add_u64 v[4:5], s[94:95], 0, v[12:13]
	s_waitcnt lgkmcnt(0)
	v_lshlrev_b32_e32 v6, 16, v8
	v_and_b32_e32 v7, 0xffff0000, v8
	v_lshlrev_b32_e32 v8, 16, v9
	v_and_b32_e32 v9, 0xffff0000, v9
	v_lshlrev_b32_e32 v12, 16, v10
	v_and_b32_e32 v13, 0xffff0000, v10
	v_lshlrev_b32_e32 v10, 16, v11
	v_and_b32_e32 v11, 0xffff0000, v11
	s_waitcnt vmcnt(12)
	v_mov_b32_e32 v0, v104
	v_mov_b32_e32 v1, v105
	v_mov_b32_e32 v2, v106
	v_mov_b32_e32 v3, v107
	v_lshlrev_b32_e32 v14, 16, v0
	v_and_b32_e32 v15, 0xffff0000, v0
	v_lshlrev_b32_e32 v0, 16, v1
	v_and_b32_e32 v1, 0xffff0000, v1
	v_lshlrev_b32_e32 v16, 16, v2
	v_and_b32_e32 v17, 0xffff0000, v2
	v_lshlrev_b32_e32 v2, 16, v3
	v_and_b32_e32 v3, 0xffff0000, v3
	v_mul_f32_e32 v18, 0xbfb8aa3b, v14
	v_mul_f32_e32 v19, 0xbfb8aa3b, v15
	v_mul_f32_e32 v20, 0xbfb8aa3b, v0
	v_mul_f32_e32 v21, 0xbfb8aa3b, v1
	v_mul_f32_e32 v22, 0xbfb8aa3b, v16
	v_mul_f32_e32 v23, 0xbfb8aa3b, v17
	v_mul_f32_e32 v24, 0xbfb8aa3b, v2
	v_mul_f32_e32 v25, 0xbfb8aa3b, v3
	v_exp_f32_e32 v18, v18
	v_exp_f32_e32 v19, v19
	v_exp_f32_e32 v20, v20
	v_exp_f32_e32 v21, v21
	v_exp_f32_e32 v22, v22
	v_exp_f32_e32 v23, v23
	v_exp_f32_e32 v24, v24
	v_exp_f32_e32 v25, v25
	v_add_f32_e32 v18, 1.0, v18
	v_add_f32_e32 v19, 1.0, v19
	v_add_f32_e32 v20, 1.0, v20
	v_add_f32_e32 v21, 1.0, v21
	v_add_f32_e32 v22, 1.0, v22
	v_add_f32_e32 v23, 1.0, v23
	v_add_f32_e32 v24, 1.0, v24
	v_add_f32_e32 v25, 1.0, v25
	v_rcp_f32_e32 v18, v18
	v_rcp_f32_e32 v19, v19
	v_rcp_f32_e32 v20, v20
	v_rcp_f32_e32 v21, v21
	v_rcp_f32_e32 v22, v22
	v_rcp_f32_e32 v23, v23
	v_rcp_f32_e32 v24, v24
	v_rcp_f32_e32 v25, v25
	v_pk_mul_f32 v[14:15], v[18:19], v[14:15]
	v_pk_mul_f32 v[0:1], v[20:21], v[0:1]
	v_pk_mul_f32 v[16:17], v[22:23], v[16:17]
	v_pk_mul_f32 v[2:3], v[24:25], v[2:3]
	v_pk_mul_f32 v[6:7], v[14:15], v[6:7]
	v_pk_mul_f32 v[8:9], v[0:1], v[8:9]
	v_pk_mul_f32 v[12:13], v[16:17], v[12:13]
	v_pk_mul_f32 v[10:11], v[2:3], v[10:11]
	v_cvt_pk_bf16_f32 v0, v6, v7
	v_cvt_pk_bf16_f32 v1, v8, v9
	v_cvt_pk_bf16_f32 v2, v12, v13
	v_cvt_pk_bf16_f32 v3, v10, v11
	global_store_dwordx4 v[4:5], v[0:3], off
	s_cbranch_scc1 .LBB0_352
	s_lshr_b32 s41, s41, 1
	s_lshr_b32 s46, s46, 6
	s_cmp_ge_u32 s46, s41
	s_barrier
	s_waitcnt vmcnt(7)
	ds_write_b128 v160, v[88:91] offset:9216
	ds_write_b128 v160, v[80:83]
	ds_write_b128 v160, v[84:87] offset:4608
	s_waitcnt vmcnt(6)
	ds_write_b128 v160, v[92:95] offset:13824
	s_waitcnt vmcnt(4)
	v_mov_b32_e32 v0, v218
	v_mov_b32_e32 v1, v219
	v_mov_b32_e32 v2, v220
	v_mov_b32_e32 v3, v221
	v_mov_b32_e32 v4, v222
	v_mov_b32_e32 v5, v223
	v_mov_b32_e32 v6, v224
	v_mov_b32_e32 v7, v225
	v_mov_b32_e32 v8, v226
	v_mov_b32_e32 v9, v227
	v_mov_b32_e32 v10, v228
	v_mov_b32_e32 v12, v230
	v_mov_b32_e32 v13, v231
	s_cbranch_scc1 .LBB0_344
	s_branch .Lmy_sw338_cont

; DI void kv64_fetch(KVR& R, const bf16_t* kbase, int kstride, const bf16_t* vtbase, int vtstride, int key0, bool withV, int tid) {
;   const int row0 = tid >> 3, kc = tid & 7, row1 = row0 + 32;
;   R.k0 = ldg16(kbase + (size_t)(key0 + row0) * kstride + kc * 8);
;   R.k1 = ldg16(kbase + (size_t)(key0 + row1) * kstride + kc * 8);
;   if (withV) { R.v0 = ldg16(vtbase + (size_t)row0 * vtstride + key0 + kc * 8); R.v1 = ldg16(vtbase + (size_t)row1 * vtstride + key0 + kc * 8); }
; }
.Lmy_sw338_cont:
	s_add_i32 s0, s38, 64
	v_or_b32_e32 v128, s0, v158
	v_lshlrev_b64 v[12:13], 9, v[128:129]
	v_or_b32_e32 v128, s0, v159
	v_lshl_add_u64 v[12:13], v[0:1], 0, v[12:13]
	v_lshlrev_b64 v[14:15], 9, v[128:129]
	v_lshl_add_u64 v[12:13], v[12:13], 0, v[142:143]
	v_lshl_add_u64 v[14:15], v[0:1], 0, v[14:15]
	v_lshl_add_u64 v[14:15], v[14:15], 0, v[142:143]
	global_load_dwordx4 v[80:83], v[12:13], off
	global_load_dwordx4 v[84:87], v[14:15], off
	global_load_dwordx4 v[88:91], v[6:7], off offset:128
	global_load_dwordx4 v[92:95], v[8:9], off offset:128

; DI void phase_attn_swa(const Params& P, const float* sinks, bf16_t* og, unsigned char* smem, int L, int G) {
;     ...
;   for (int it = L; it < 4096; it += G) {
;     int qt, bg; gqa_item(it, L, G, gi, qt, bg);
;     const int b = bg >> 2, g = bg & 3;
;     const int t0 = qt * 32, t = t0 + r, head = g * 4 + w;
;     const size_t tok = (size_t)b * SEQ + t;
;     bf16x8 qf[4];
; #pragma unroll
;     for (int ks = 0; ks < 4; ++ks) qf[ks] = *(const bf16x8*)(big + SW_Q + tok * 1024 + head * 64 + ks * 16 + 8 * h);
;     f32x16 o0, o1, s[2]; o_zero(o0, o1);
;     float m = sinks[head] * LOG2E, l = 1.f;
;     const bf16_t* kb = big + SW_K + (size_t)b * SEQ * 256 + g * 64;
;     const bf16_t* vb = big + SW_VT + (size_t)((b * 4 + g) * 64) * SEQ;
;     const int jlo = (t0 - 127 > 0 ? t0 - 127 : 0) >> 6, jhi = (t0 + 31) >> 6;
;     KVR R; kv64_fetch(R, kb, 256, vb, SEQ, jlo * 64, true, tid);
;     __syncthreads();
;     kv64_store(R, sK, sVt, tid);
;     if (jlo < jhi) kv64_fetch(R, kb, 256, vb, SEQ, jlo * 64 + 64, true, tid);
.LBB0_1659:
	s_mov_b32 s11, s9
	v_lshlrev_b32_e32 v35, 6, v173
	v_lshl_add_u64 v[32:33], v[148:149], 0, s[10:11]
	v_or_b32_e32 v35, v35, v130
	v_or_b32_e32 v36, v32, v132
	v_mov_b32_e32 v37, v33
	v_lshlrev_b64 v[40:41], 11, v[36:37]
	v_lshlrev_b32_e32 v35, 1, v35
	v_or_b32_e32 v40, v40, v35
	v_lshl_add_u64 v[36:37], s[6:7], 0, v[40:41]
	v_mov_b32_e32 v254, 0x4000
	v_mov_b32_e32 v255, 0
	v_lshl_add_u64 v[248:249], v[36:37], 0, v[254:255]
	v_lshl_add_u64 v[250:251], v[248:249], 0, v[254:255]
	v_lshl_add_u64 v[252:253], v[250:251], 0, v[254:255]
	global_load_dwordx4 v[36:39], v[36:37], off
	global_load_dwordx4 v[96:99], v[248:249], off
	global_load_dwordx4 v[100:103], v[250:251], off
	global_load_dwordx4 v[104:107], v[252:253], off
	s_add_i32 s98, s16, s74
	s_cmpk_gt_i32 s98, 0xfff
	s_cbranch_scc1 .Lmy_sw1660_nopf
	s_and_b64 vcc, exec, s[2:3]
	s_cbranch_vccz .Lmy_sw1660_1662
	s_ashr_i32 s100, s98, 6
	s_sub_i32 s11, 63, s100
	s_lshl_b32 s100, s98, 1
	s_and_b32 s100, s100, 0x7e
	v_add_u32_e32 v220, s100, v131
	s_cbranch_execz .Lmy_sw1660_1663
	s_branch .Lmy_sw1660_1664
.Lmy_sw1660_1662:
.Lmy_sw1660_1663:
	s_ashr_i32 s100, s98, 8
	s_and_b32 s100, s100, -2
	s_bitcmp0_b32 s98, 8
	v_add_u32_e32 v220, s100, v139
	s_cselect_b32 s11, s12, s13
.Lmy_sw1660_1664:
	v_ashrrev_i32_e32 v218, 2, v220
	s_lshl_b32 s10, s11, 5
	v_ashrrev_i32_e32 v219, 31, v218
	v_or_b32_e32 v150, s10, v135
	v_lshlrev_b64 v[148:149], 11, v[218:219]
	v_mov_b32_e32 v151, v129
	v_and_b32_e32 v221, 3, v220
	v_lshl_add_u64 v[222:223], v[148:149], 0, v[150:151]
	v_lshl_or_b32 v173, v221, 2, v133
	v_lshlrev_b64 v[222:223], 11, v[222:223]
	s_max_i32 s100, s10, 0x7f
	v_lshl_add_u64 v[222:223], s[76:77], 0, v[222:223]
	v_lshlrev_b32_e32 v128, 7, v173
	v_lshlrev_b64 v[218:219], 20, v[218:219]
	v_lshlrev_b32_e32 v220, 6, v220
	s_add_i32 s17, s100, 0xffffff81
	v_lshl_add_u64 v[222:223], v[222:223], 0, v[128:129]
	v_lshl_add_u64 v[218:219], s[66:67], 0, v[218:219]
	v_lshlrev_b32_e32 v128, 7, v221
	v_ashrrev_i32_e32 v221, 31, v220
	s_and_b32 s8, s17, 0xffffffc0
	v_lshl_add_u64 v[230:231], v[222:223], 0, v[140:141]
	v_lshlrev_b32_e32 v222, 2, v173
	v_lshl_add_u64 v[218:219], v[218:219], 0, v[128:129]
	v_lshlrev_b64 v[220:221], 12, v[220:221]
	v_or_b32_e32 v128, s8, v158
	global_load_dwordx4 v[64:67], v[230:231], off
	global_load_dwordx4 v[68:71], v[230:231], off offset:32
	global_load_dword v228, v222, s[92:93]
	v_lshl_add_u64 v[222:223], s[4:5], 0, v[220:221]
	v_lshlrev_b64 v[220:221], 9, v[128:129]
	v_or_b32_e32 v128, s8, v159
	v_lshl_add_u64 v[220:221], v[218:219], 0, v[220:221]
	v_lshlrev_b64 v[224:225], 9, v[128:129]
	v_lshl_add_u64 v[220:221], v[220:221], 0, v[142:143]
	v_lshl_add_u64 v[224:225], v[218:219], 0, v[224:225]
	v_lshl_add_u64 v[224:225], v[224:225], 0, v[142:143]
	global_load_dwordx4 v[80:83], v[220:221], off
	global_load_dwordx4 v[84:87], v[224:225], off
	v_lshl_add_u64 v[220:221], v[222:223], 0, v[144:145]
	s_lshl_b64 s[100:101], s[8:9], 1
	v_lshl_add_u64 v[224:225], v[220:221], 0, s[100:101]
	v_lshl_add_u64 v[224:225], v[224:225], 0, v[142:143]
	v_lshl_add_u64 v[222:223], v[222:223], 0, v[146:147]
	global_load_dwordx4 v[88:91], v[224:225], off
	v_lshl_add_u64 v[226:227], v[222:223], 0, s[100:101]
	v_lshl_add_u64 v[226:227], v[226:227], 0, v[142:143]
	global_load_dwordx4 v[92:95], v[226:227], off
	global_load_dwordx4 v[72:75], v[230:231], off offset:64
	global_load_dwordx4 v[76:79], v[230:231], off offset:96
	s_branch .Lmy_sw1660_join

; DI unsigned pack2(float a, float b) { f32x2_t v = {a, b}; bf16x2_t r = __builtin_convertvector(v, bf16x2_t); return __builtin_bit_cast(unsigned, r); }
; DI float bflo(unsigned u) { return __uint_as_float(u << 16); }
; DI float bfhi(unsigned u) { return __uint_as_float(u & 0xffff0000u); }
; DI float siluf_(float x) { return x * __builtin_amdgcn_rcpf(1.f + __expf(-x)); }
; DI void attn_write_staged(const f32x16& o0, const f32x16& o1, bf16_t* og, const bf16_t* z, size_t tok0, int head, int lane, bf16_t* wl) {
;   const int q = lane & 31, h = lane >> 5;
; #pragma unroll
;   for (int dt = 0; dt < 2; ++dt)
; #pragma unroll
;     for (int q4 = 0; q4 < 4; ++q4) {
;       const f32x16& o = dt ? o1 : o0;
;       *(uint2*)(wl + q * 72 + dt * 32 + 8 * q4 + 4 * h) = make_uint2(pack2(o[4 * q4], o[4 * q4 + 1]), pack2(o[4 * q4 + 2], o[4 * q4 + 3]));
;     }
; #pragma unroll
;   for (int k = 0; k < 4; ++k) {
;     const int ci = lane + 64 * k, row = ci >> 3, c8 = ci & 7;
;     const u32x4 ov = *(const u32x4*)(wl + row * 72 + c8 * 8);
;     const size_t off = (tok0 + row) * 1024 + head * 64 + c8 * 8;
;     const u32x4 zv = ldg16(z + off);
;     u32x4 r;
;     r.x = pack2(bflo(ov.x) * siluf_(bflo(zv.x)), bfhi(ov.x) * siluf_(bfhi(zv.x)));
;     r.y = pack2(bflo(ov.y) * siluf_(bflo(zv.y)), bfhi(ov.y) * siluf_(bfhi(zv.y)));
;     r.z = pack2(bflo(ov.z) * siluf_(bflo(zv.z)), bfhi(ov.z) * siluf_(bfhi(zv.z)));
;     r.w = pack2(bflo(ov.w) * siluf_(bflo(zv.w)), bfhi(ov.w) * siluf_(bfhi(zv.w)));
;     *(u32x4*)(og + off) = r;
;   }
; DI void phase_attn_swa(const Params& P, const float* sinks, bf16_t* og, unsigned char* smem, int L, int G) {
;     ...
;     const float il = 1.f / l;
; #pragma unroll
;     for (int q = 0; q < 16; ++q) { o0[q] *= il; o1[q] *= il; }
.Lmy_sw1660_join:
	v_div_scale_f32 v42, s[0:1], v34, v34, 1.0
	v_rcp_f32_e32 v43, v42
	v_div_scale_f32 v44, vcc, 1.0, v34, 1.0
	v_add_u32_e32 v45, 0xa000, v166
	v_fma_f32 v46, -v42, v43, 1.0
	v_fmac_f32_e32 v43, v46, v43
	v_mul_f32_e32 v46, v44, v43
	v_fma_f32 v47, -v42, v46, v44
	v_fmac_f32_e32 v46, v47, v43
	v_fma_f32 v42, -v42, v46, v44
	v_div_fmas_f32 v42, v42, v43, v46
	v_div_fixup_f32 v34, v42, v34, 1.0
	v_pk_mul_f32 v[0:1], v[34:35], v[0:1] op_sel_hi:[0,1]
	v_pk_mul_f32 v[2:3], v[34:35], v[2:3] op_sel_hi:[0,1]
	v_pk_mul_f32 v[4:5], v[34:35], v[4:5] op_sel_hi:[0,1]
	v_pk_mul_f32 v[20:21], v[20:21], v[34:35] op_sel_hi:[1,0]
	v_pk_mul_f32 v[6:7], v[34:35], v[6:7] op_sel_hi:[0,1]
	v_pk_mul_f32 v[22:23], v[22:23], v[34:35] op_sel_hi:[1,0]
	v_pk_mul_f32 v[24:25], v[24:25], v[34:35] op_sel_hi:[1,0]
	v_pk_mul_f32 v[10:11], v[34:35], v[10:11] op_sel_hi:[0,1]
	v_pk_mul_f32 v[26:27], v[26:27], v[34:35] op_sel_hi:[1,0]
	v_pk_mul_f32 v[12:13], v[34:35], v[12:13] op_sel_hi:[0,1]
	v_pk_mul_f32 v[16:17], v[16:17], v[34:35] op_sel_hi:[1,0]
	v_pk_mul_f32 v[18:19], v[18:19], v[34:35] op_sel_hi:[1,0]
	v_pk_mul_f32 v[8:9], v[34:35], v[8:9] op_sel_hi:[0,1]
	v_pk_mul_f32 v[28:29], v[28:29], v[34:35] op_sel_hi:[1,0]
	v_pk_mul_f32 v[14:15], v[34:35], v[14:15] op_sel_hi:[0,1]
	v_pk_mul_f32 v[30:31], v[30:31], v[34:35] op_sel_hi:[1,0]
	v_cvt_pk_bf16_f32 v0, v0, v1
	v_cvt_pk_bf16_f32 v1, v2, v3
	v_cvt_pk_bf16_f32 v2, v4, v5
	v_cvt_pk_bf16_f32 v3, v6, v7
	v_cvt_pk_bf16_f32 v5, v10, v11
	v_cvt_pk_bf16_f32 v6, v12, v13
	v_cvt_pk_bf16_f32 v10, v20, v21
	v_cvt_pk_bf16_f32 v11, v22, v23
	v_cvt_pk_bf16_f32 v12, v24, v25
	v_cvt_pk_bf16_f32 v13, v26, v27
	v_cvt_pk_bf16_f32 v4, v8, v9
	v_cvt_pk_bf16_f32 v7, v14, v15
	v_cvt_pk_bf16_f32 v8, v16, v17
	v_cvt_pk_bf16_f32 v9, v18, v19
	v_cvt_pk_bf16_f32 v14, v28, v29
	v_cvt_pk_bf16_f32 v15, v30, v31
	ds_write2_b64 v45, v[0:1], v[2:3] offset1:2
	ds_write2_b64 v45, v[4:5], v[6:7] offset0:4 offset1:6
	ds_write2_b64 v45, v[8:9], v[10:11] offset0:8 offset1:10
	ds_write2_b64 v45, v[12:13], v[14:15] offset0:12 offset1:14
	ds_read_b128 v[0:3], v167 offset:40960
	ds_read_b128 v[4:7], v167 offset:42112
	s_add_i32 s16, s16, s74
	s_cmpk_gt_i32 s16, 0xfff
	s_waitcnt lgkmcnt(1)
	v_lshlrev_b32_e32 v8, 16, v0
	v_and_b32_e32 v9, 0xffff0000, v0
	v_lshlrev_b32_e32 v0, 16, v1
	v_and_b32_e32 v1, 0xffff0000, v1
	s_waitcnt vmcnt(12)
	v_lshlrev_b32_e32 v10, 16, v36
	v_and_b32_e32 v11, 0xffff0000, v36
	v_lshlrev_b32_e32 v12, 16, v37
	v_and_b32_e32 v13, 0xffff0000, v37
	v_mul_f32_e32 v16, 0xbfb8aa3b, v10
	v_mul_f32_e32 v17, 0xbfb8aa3b, v11
	v_mul_f32_e32 v18, 0xbfb8aa3b, v12
	v_mul_f32_e32 v19, 0xbfb8aa3b, v13
	v_exp_f32_e32 v16, v16
	v_exp_f32_e32 v17, v17
	v_exp_f32_e32 v18, v18
	v_exp_f32_e32 v19, v19
	v_lshlrev_b32_e32 v14, 16, v38
	v_and_b32_e32 v15, 0xffff0000, v38
	v_add_f32_e32 v16, 1.0, v16
	v_add_f32_e32 v17, 1.0, v17
	v_add_f32_e32 v18, 1.0, v18
	v_add_f32_e32 v19, 1.0, v19
	v_mul_f32_e32 v20, 0xbfb8aa3b, v14
	v_mul_f32_e32 v21, 0xbfb8aa3b, v15
	v_rcp_f32_e32 v16, v16
	v_rcp_f32_e32 v17, v17
	v_rcp_f32_e32 v18, v18
	v_rcp_f32_e32 v19, v19
	v_exp_f32_e32 v20, v20
	v_exp_f32_e32 v21, v21
	v_pk_mul_f32 v[10:11], v[16:17], v[10:11]
	v_pk_mul_f32 v[12:13], v[18:19], v[12:13]
	v_add_f32_e32 v20, 1.0, v20
	v_pk_mul_f32 v[8:9], v[10:11], v[8:9]
	v_pk_mul_f32 v[10:11], v[12:13], v[0:1]
	v_add_f32_e32 v1, 1.0, v21
	v_rcp_f32_e32 v20, v20
	v_rcp_f32_e32 v21, v1
	v_lshlrev_b32_e32 v12, 16, v39
	v_cvt_pk_bf16_f32 v0, v8, v9
	v_lshlrev_b32_e32 v8, 16, v2
	v_and_b32_e32 v9, 0xffff0000, v2
	v_and_b32_e32 v13, 0xffff0000, v39
	v_mul_f32_e32 v2, 0xbfb8aa3b, v12
	v_cvt_pk_bf16_f32 v1, v10, v11
	v_pk_mul_f32 v[10:11], v[20:21], v[14:15]
	v_exp_f32_e32 v2, v2
	v_mul_f32_e32 v14, 0xbfb8aa3b, v13
	v_exp_f32_e32 v14, v14
	v_pk_mul_f32 v[8:9], v[10:11], v[8:9]
	v_add_f32_e32 v2, 1.0, v2
	v_rcp_f32_e32 v10, v2
	v_add_f32_e32 v2, 1.0, v14
	v_rcp_f32_e32 v11, v2
	v_cvt_pk_bf16_f32 v2, v8, v9
	v_lshlrev_b32_e32 v8, 16, v3
	v_and_b32_e32 v9, 0xffff0000, v3
	v_pk_mul_f32 v[10:11], v[10:11], v[12:13]
	s_waitcnt lgkmcnt(0)
	v_lshlrev_b32_e32 v12, 16, v4
	v_pk_mul_f32 v[8:9], v[10:11], v[8:9]
	v_or_b32_e32 v10, v32, v136
	v_cvt_pk_bf16_f32 v3, v8, v9
	v_lshl_add_u64 v[8:9], s[94:95], 0, v[40:41]
	global_store_dwordx4 v[8:9], v[0:3], off
	v_mov_b32_e32 v11, v33
	v_and_b32_e32 v13, 0xffff0000, v4
	v_or_b32_e32 v0, v32, v134
	v_mov_b32_e32 v1, v33
	v_lshlrev_b64 v[8:9], 11, v[0:1]
	v_or_b32_e32 v8, v8, v35
	v_lshl_add_u64 v[0:1], s[6:7], 0, v[8:9]
	v_lshlrev_b32_e32 v4, 16, v5
	v_and_b32_e32 v5, 0xffff0000, v5
	v_lshlrev_b32_e32 v14, 16, v6
	v_and_b32_e32 v15, 0xffff0000, v6
	v_lshlrev_b32_e32 v6, 16, v7
	v_and_b32_e32 v7, 0xffff0000, v7
	v_lshlrev_b64 v[10:11], 11, v[10:11]
	v_lshl_add_u64 v[8:9], s[94:95], 0, v[8:9]
	v_or_b32_e32 v10, v10, v35
	v_or_b32_e32 v32, v32, v138
	s_waitcnt vmcnt(12)
; DI unsigned pack2(float a, float b) { f32x2_t v = {a, b}; bf16x2_t r = __builtin_convertvector(v, bf16x2_t); return __builtin_bit_cast(unsigned, r); }
; DI float bflo(unsigned u) { return __uint_as_float(u << 16); }
; DI float bfhi(unsigned u) { return __uint_as_float(u & 0xffff0000u); }
; DI float siluf_(float x) { return x * __builtin_amdgcn_rcpf(1.f + __expf(-x)); }
; DI void attn_write_staged(const f32x16& o0, const f32x16& o1, bf16_t* og, const bf16_t* z, size_t tok0, int head, int lane, bf16_t* wl) {
;     ...
; #pragma unroll
;   for (int k = 0; k < 4; ++k) {
;     const int ci = lane + 64 * k, row = ci >> 3, c8 = ci & 7;
;     const u32x4 ov = *(const u32x4*)(wl + row * 72 + c8 * 8);
;     const size_t off = (tok0 + row) * 1024 + head * 64 + c8 * 8;
;     const u32x4 zv = ldg16(z + off);
;     u32x4 r;
;     r.x = pack2(bflo(ov.x) * siluf_(bflo(zv.x)), bfhi(ov.x) * siluf_(bfhi(zv.x)));
;     r.y = pack2(bflo(ov.y) * siluf_(bflo(zv.y)), bfhi(ov.y) * siluf_(bfhi(zv.y)));
;     r.z = pack2(bflo(ov.z) * siluf_(bflo(zv.z)), bfhi(ov.z) * siluf_(bfhi(zv.z)));
;     r.w = pack2(bflo(ov.w) * siluf_(bflo(zv.w)), bfhi(ov.w) * siluf_(bfhi(zv.w)));
;     *(u32x4*)(og + off) = r;
;   }
; DI void phase_attn_swa(const Params& P, const float* sinks, bf16_t* og, unsigned char* smem, int L, int G) {
;     ...
;     __syncthreads();
;     kv64_store(R, sK, sVt, tid);
;     if (jlo < jhi) kv64_fetch(R, kb, 256, vb, SEQ, jlo * 64 + 64, true, tid);
	v_mov_b32_e32 v0, v96
	v_mov_b32_e32 v1, v97
	v_mov_b32_e32 v2, v98
	v_mov_b32_e32 v3, v99
	v_lshlrev_b32_e32 v16, 16, v0
	v_and_b32_e32 v17, 0xffff0000, v0
	v_lshlrev_b32_e32 v0, 16, v1
	v_and_b32_e32 v1, 0xffff0000, v1
	v_lshlrev_b32_e32 v18, 16, v2
	v_and_b32_e32 v19, 0xffff0000, v2
	v_lshlrev_b32_e32 v2, 16, v3
	v_and_b32_e32 v3, 0xffff0000, v3
	v_mul_f32_e32 v20, 0xbfb8aa3b, v16
	v_mul_f32_e32 v21, 0xbfb8aa3b, v17
	v_mul_f32_e32 v22, 0xbfb8aa3b, v0
	v_mul_f32_e32 v23, 0xbfb8aa3b, v1
	v_mul_f32_e32 v24, 0xbfb8aa3b, v18
	v_mul_f32_e32 v25, 0xbfb8aa3b, v19
	v_mul_f32_e32 v26, 0xbfb8aa3b, v2
	v_mul_f32_e32 v27, 0xbfb8aa3b, v3
	v_exp_f32_e32 v20, v20
	v_exp_f32_e32 v21, v21
	v_exp_f32_e32 v22, v22
	v_exp_f32_e32 v23, v23
	v_exp_f32_e32 v24, v24
	v_exp_f32_e32 v25, v25
	v_exp_f32_e32 v26, v26
	v_exp_f32_e32 v27, v27
	v_add_f32_e32 v20, 1.0, v20
	v_add_f32_e32 v21, 1.0, v21
	v_add_f32_e32 v22, 1.0, v22
	v_add_f32_e32 v23, 1.0, v23
	v_add_f32_e32 v24, 1.0, v24
	v_add_f32_e32 v25, 1.0, v25
	v_add_f32_e32 v26, 1.0, v26
	v_add_f32_e32 v27, 1.0, v27
	v_rcp_f32_e32 v20, v20
	v_rcp_f32_e32 v21, v21
	v_rcp_f32_e32 v22, v22
	v_rcp_f32_e32 v23, v23
	v_rcp_f32_e32 v24, v24
	v_rcp_f32_e32 v25, v25
	v_rcp_f32_e32 v26, v26
	v_rcp_f32_e32 v27, v27
	v_pk_mul_f32 v[16:17], v[20:21], v[16:17]
	v_pk_mul_f32 v[0:1], v[22:23], v[0:1]
	v_pk_mul_f32 v[18:19], v[24:25], v[18:19]
	v_pk_mul_f32 v[2:3], v[26:27], v[2:3]
	v_pk_mul_f32 v[12:13], v[16:17], v[12:13]
	v_pk_mul_f32 v[4:5], v[0:1], v[4:5]
	v_pk_mul_f32 v[14:15], v[18:19], v[14:15]
	v_pk_mul_f32 v[6:7], v[2:3], v[6:7]
	v_cvt_pk_bf16_f32 v0, v12, v13
	v_cvt_pk_bf16_f32 v1, v4, v5
	v_cvt_pk_bf16_f32 v2, v14, v15
	v_cvt_pk_bf16_f32 v3, v6, v7
	global_store_dwordx4 v[8:9], v[0:3], off
	v_lshlrev_b64 v[12:13], 11, v[32:33]
	ds_read_b128 v[4:7], v167 offset:43264
	v_lshl_add_u64 v[0:1], s[6:7], 0, v[10:11]
	v_lshl_add_u64 v[14:15], s[94:95], 0, v[10:11]
	ds_read_b128 v[8:11], v167 offset:44416
	s_waitcnt lgkmcnt(1)
	v_lshlrev_b32_e32 v18, 16, v4
	v_and_b32_e32 v19, 0xffff0000, v4
	v_lshlrev_b32_e32 v4, 16, v5
	v_and_b32_e32 v5, 0xffff0000, v5
	v_lshlrev_b32_e32 v20, 16, v6
	v_and_b32_e32 v21, 0xffff0000, v6
	v_lshlrev_b32_e32 v6, 16, v7
	v_and_b32_e32 v7, 0xffff0000, v7
	v_or_b32_e32 v12, v12, v35
	v_lshl_add_u64 v[16:17], s[6:7], 0, v[12:13]
	s_waitcnt vmcnt(12)
	v_mov_b32_e32 v0, v100
	v_mov_b32_e32 v1, v101
	v_mov_b32_e32 v2, v102
	v_mov_b32_e32 v3, v103
	v_lshlrev_b32_e32 v22, 16, v0
	v_and_b32_e32 v23, 0xffff0000, v0
	v_lshlrev_b32_e32 v0, 16, v1
	v_and_b32_e32 v1, 0xffff0000, v1
	v_lshlrev_b32_e32 v24, 16, v2
	v_and_b32_e32 v25, 0xffff0000, v2
	v_lshlrev_b32_e32 v2, 16, v3
	v_and_b32_e32 v3, 0xffff0000, v3
	v_mul_f32_e32 v26, 0xbfb8aa3b, v22
	v_mul_f32_e32 v27, 0xbfb8aa3b, v23
	v_mul_f32_e32 v28, 0xbfb8aa3b, v0
	v_mul_f32_e32 v29, 0xbfb8aa3b, v1
	v_mul_f32_e32 v30, 0xbfb8aa3b, v24
	v_mul_f32_e32 v31, 0xbfb8aa3b, v25
	v_mul_f32_e32 v32, 0xbfb8aa3b, v2
	v_mul_f32_e32 v33, 0xbfb8aa3b, v3
	v_exp_f32_e32 v26, v26
	v_exp_f32_e32 v27, v27
	v_exp_f32_e32 v28, v28
	v_exp_f32_e32 v29, v29
	v_exp_f32_e32 v30, v30
	v_exp_f32_e32 v31, v31
	v_exp_f32_e32 v32, v32
	v_exp_f32_e32 v33, v33
	v_add_f32_e32 v26, 1.0, v26
	v_add_f32_e32 v27, 1.0, v27
	v_add_f32_e32 v28, 1.0, v28
	v_add_f32_e32 v29, 1.0, v29
	v_add_f32_e32 v30, 1.0, v30
	v_add_f32_e32 v31, 1.0, v31
	v_add_f32_e32 v32, 1.0, v32
	v_add_f32_e32 v33, 1.0, v33
	v_rcp_f32_e32 v26, v26
	v_rcp_f32_e32 v27, v27
	v_rcp_f32_e32 v28, v28
	v_rcp_f32_e32 v29, v29
	v_rcp_f32_e32 v30, v30
	v_rcp_f32_e32 v31, v31
	v_rcp_f32_e32 v32, v32
	v_rcp_f32_e32 v33, v33
	v_pk_mul_f32 v[22:23], v[26:27], v[22:23]
	v_pk_mul_f32 v[0:1], v[28:29], v[0:1]
	v_pk_mul_f32 v[24:25], v[30:31], v[24:25]
	v_pk_mul_f32 v[2:3], v[32:33], v[2:3]
	v_pk_mul_f32 v[18:19], v[22:23], v[18:19]
	v_pk_mul_f32 v[4:5], v[0:1], v[4:5]
	v_pk_mul_f32 v[20:21], v[24:25], v[20:21]
	v_pk_mul_f32 v[6:7], v[2:3], v[6:7]
	v_cvt_pk_bf16_f32 v0, v18, v19
	v_cvt_pk_bf16_f32 v1, v4, v5
	v_cvt_pk_bf16_f32 v2, v20, v21
	v_cvt_pk_bf16_f32 v3, v6, v7
	global_store_dwordx4 v[14:15], v[0:3], off
	v_lshl_add_u64 v[4:5], s[94:95], 0, v[12:13]
	s_waitcnt lgkmcnt(0)
	v_lshlrev_b32_e32 v6, 16, v8
	v_and_b32_e32 v7, 0xffff0000, v8
	v_lshlrev_b32_e32 v8, 16, v9
	v_and_b32_e32 v9, 0xffff0000, v9
	v_lshlrev_b32_e32 v12, 16, v10
	v_and_b32_e32 v13, 0xffff0000, v10
	v_lshlrev_b32_e32 v10, 16, v11
	v_and_b32_e32 v11, 0xffff0000, v11
	s_waitcnt vmcnt(12)
	v_mov_b32_e32 v0, v104
	v_mov_b32_e32 v1, v105
	v_mov_b32_e32 v2, v106
	v_mov_b32_e32 v3, v107
	v_lshlrev_b32_e32 v14, 16, v0
	v_and_b32_e32 v15, 0xffff0000, v0
	v_lshlrev_b32_e32 v0, 16, v1
	v_and_b32_e32 v1, 0xffff0000, v1
	v_lshlrev_b32_e32 v16, 16, v2
	v_and_b32_e32 v17, 0xffff0000, v2
	v_lshlrev_b32_e32 v2, 16, v3
	v_and_b32_e32 v3, 0xffff0000, v3
	v_mul_f32_e32 v18, 0xbfb8aa3b, v14
	v_mul_f32_e32 v19, 0xbfb8aa3b, v15
	v_mul_f32_e32 v20, 0xbfb8aa3b, v0
	v_mul_f32_e32 v21, 0xbfb8aa3b, v1
	v_mul_f32_e32 v22, 0xbfb8aa3b, v16
	v_mul_f32_e32 v23, 0xbfb8aa3b, v17
	v_mul_f32_e32 v24, 0xbfb8aa3b, v2
	v_mul_f32_e32 v25, 0xbfb8aa3b, v3
	v_exp_f32_e32 v18, v18
	v_exp_f32_e32 v19, v19
	v_exp_f32_e32 v20, v20
	v_exp_f32_e32 v21, v21
	v_exp_f32_e32 v22, v22
	v_exp_f32_e32 v23, v23
	v_exp_f32_e32 v24, v24
	v_exp_f32_e32 v25, v25
	v_add_f32_e32 v18, 1.0, v18
	v_add_f32_e32 v19, 1.0, v19
	v_add_f32_e32 v20, 1.0, v20
	v_add_f32_e32 v21, 1.0, v21
	v_add_f32_e32 v22, 1.0, v22
	v_add_f32_e32 v23, 1.0, v23
	v_add_f32_e32 v24, 1.0, v24
	v_add_f32_e32 v25, 1.0, v25
	v_rcp_f32_e32 v18, v18
	v_rcp_f32_e32 v19, v19
	v_rcp_f32_e32 v20, v20
	v_rcp_f32_e32 v21, v21
	v_rcp_f32_e32 v22, v22
	v_rcp_f32_e32 v23, v23
	v_rcp_f32_e32 v24, v24
	v_rcp_f32_e32 v25, v25
	v_pk_mul_f32 v[14:15], v[18:19], v[14:15]
	v_pk_mul_f32 v[0:1], v[20:21], v[0:1]
	v_pk_mul_f32 v[16:17], v[22:23], v[16:17]
	v_pk_mul_f32 v[2:3], v[24:25], v[2:3]
	v_pk_mul_f32 v[6:7], v[14:15], v[6:7]
	v_pk_mul_f32 v[8:9], v[0:1], v[8:9]
	v_pk_mul_f32 v[12:13], v[16:17], v[12:13]
	v_pk_mul_f32 v[10:11], v[2:3], v[10:11]
	v_cvt_pk_bf16_f32 v0, v6, v7
	v_cvt_pk_bf16_f32 v1, v8, v9
	v_cvt_pk_bf16_f32 v2, v12, v13
	v_cvt_pk_bf16_f32 v3, v10, v11
	global_store_dwordx4 v[4:5], v[0:3], off
	s_cbranch_scc1 .LBB0_1674
	s_lshr_b32 s11, s11, 1
	s_lshr_b32 s17, s17, 6
	s_cmp_ge_u32 s17, s11
	s_barrier
	s_waitcnt vmcnt(7)
	ds_write_b128 v160, v[88:91] offset:9216
	ds_write_b128 v160, v[80:83]
	ds_write_b128 v160, v[84:87] offset:4608
	s_waitcnt vmcnt(6)
	ds_write_b128 v160, v[92:95] offset:13824
	s_waitcnt vmcnt(4)
	v_mov_b32_e32 v0, v218
	v_mov_b32_e32 v1, v219
	v_mov_b32_e32 v2, v220
	v_mov_b32_e32 v3, v221
	v_mov_b32_e32 v4, v222
	v_mov_b32_e32 v5, v223
	v_mov_b32_e32 v6, v224
	v_mov_b32_e32 v7, v225
	v_mov_b32_e32 v8, v226
	v_mov_b32_e32 v9, v227
	v_mov_b32_e32 v10, v228
	v_mov_b32_e32 v12, v230
	v_mov_b32_e32 v13, v231
	s_cbranch_scc1 .LBB0_1666
	s_branch .Lmy_sw1660_cont

; DI void kv64_fetch(KVR& R, const bf16_t* kbase, int kstride, const bf16_t* vtbase, int vtstride, int key0, bool withV, int tid) {
;   const int row0 = tid >> 3, kc = tid & 7, row1 = row0 + 32;
;   R.k0 = ldg16(kbase + (size_t)(key0 + row0) * kstride + kc * 8);
;   R.k1 = ldg16(kbase + (size_t)(key0 + row1) * kstride + kc * 8);
;   if (withV) { R.v0 = ldg16(vtbase + (size_t)row0 * vtstride + key0 + kc * 8); R.v1 = ldg16(vtbase + (size_t)row1 * vtstride + key0 + kc * 8); }
; }
.Lmy_sw1660_cont:
	s_add_i32 s0, s8, 64
	v_or_b32_e32 v128, s0, v158
	v_lshlrev_b64 v[12:13], 9, v[128:129]
	v_or_b32_e32 v128, s0, v159
	v_lshl_add_u64 v[12:13], v[0:1], 0, v[12:13]
	v_lshlrev_b64 v[14:15], 9, v[128:129]
	v_lshl_add_u64 v[12:13], v[12:13], 0, v[142:143]
	v_lshl_add_u64 v[14:15], v[0:1], 0, v[14:15]
	v_lshl_add_u64 v[14:15], v[14:15], 0, v[142:143]
	global_load_dwordx4 v[80:83], v[12:13], off
	global_load_dwordx4 v[84:87], v[14:15], off
	global_load_dwordx4 v[88:91], v[6:7], off offset:128
	global_load_dwordx4 v[92:95], v[8:9], off offset:128
